# GEMM phase prologues (P1/P3/P4/P5): K-tile 1's six LDS-DMA loads issued before the first wait+barrier (one counted wait vmcnt(8) instead of vmcnt(2) ahead of them), on top of v35
# speedup vs baseline: 1.0146x; 1.0146x over previous
; #define PG8_STAGE(bufoff, gbase, voff) do { _Pragma("unroll") for (int _i = 0; _i < 2; ++_i) \
;         __builtin_amdgcn_global_load_lds((const unsigned*)((const char*)(gbase) + (voff)[_i]), (PG8_LAS unsigned*)(lds + (bufoff) + ldsw + _i * 8192), 16, 0, 0); } while (0)
; #define PG8_WAIT_V(n) asm volatile("s_waitcnt vmcnt(" #n ")" ::: "memory")
; #define PG8_BAR __builtin_amdgcn_s_barrier()
; template <class Epi, class Sched, bool ALIGN_EPI = false, bool SP2 = false>
; __device__ __forceinline__ void gemm_phase(PG8_LAS unsigned char* lds, const Gemm g, const Sched& S, const Epi& E) {
;     ...
;         PG8_STAGE(PG8_SB(0, 0), cB, voffB); PG8_STAGE(PG8_SB(0, 1), cB + hstep, voffB); PG8_STAGE(PG8_SA(0, 0), cA, voffA); PG8_STAGE(PG8_SA(0, 1), cA + hstep, voffA);
;         if (wr == 1) PG8_BAR;
;         PG8_WAIT_V(2); PG8_BAR;
;         PG8_STAGE(PG8_SB(1, 0), cB + kstep, voffB); PG8_STAGE(PG8_SA(1, 0), cA + kstep, voffA); PG8_STAGE(PG8_SB(1, 1), cB + hstep + kstep, voffB);
;         PG8_WAIT_V(6); PG8_BAR;
.LBB0_142:
	s_mov_b64 s[58:59], 0x4000
	s_add_i32 m0, s68, 0x18000
	v_lshl_add_u64 v[6:7], v[2:3], 0, s[58:59]
	s_mov_b64 s[60:61], 0x6000
	global_load_lds_dwordx4 v[6:7], off
	v_lshl_add_u64 v[6:7], v[2:3], 0, s[60:61]
	s_add_i32 m0, s68, 0x1a000
	s_add_i32 s73, s68, 0x8000
	global_load_lds_dwordx4 v[6:7], off
	v_lshl_add_u64 v[6:7], v[4:5], 0, s[58:59]
	s_mov_b32 m0, s73
	s_add_i32 s74, s68, 0xa000
	global_load_lds_dwordx4 v[6:7], off
	v_lshl_add_u64 v[4:5], v[4:5], 0, s[60:61]
	s_mov_b32 m0, s74
	s_mov_b64 s[62:63], 0x44000
	global_load_lds_dwordx4 v[4:5], off
	s_add_i32 m0, s68, 0x1c000
	v_lshl_add_u64 v[4:5], v[2:3], 0, s[62:63]
	s_mov_b64 s[64:65], 0x46000
	global_load_lds_dwordx4 v[4:5], off
	v_lshl_add_u64 v[2:3], v[2:3], 0, s[64:65]
	s_add_i32 m0, s68, 0x1e000
	v_and_b32_e32 v4, 48, v0
	global_load_lds_dwordx4 v[2:3], off
	s_waitcnt vmcnt(8)
	s_barrier
	v_and_b32_e32 v2, 15, v0
	v_lshlrev_b32_e32 v5, 2, v0
	s_and_b32 s75, s3, 3
	v_lshl_or_b32 v1, s2, 6, v2
	s_lshl_b32 s2, s2, 13
	v_lshl_or_b32 v2, v2, 6, v4
	v_and_b32_e32 v5, 32, v5
	v_bitop3_b32 v2, v2, s2, v5 bitop3:0xde
	s_lshl_b32 s2, s75, 12
	s_cmpk_lt_u32 s10, 0x100
	v_readlane_b32 s4, v251, 3
	s_cselect_b64 s[66:67], -1, 0
	s_ashr_i32 s89, s4, 31
	s_ashr_i32 s92, s96, 31
	v_readlane_b32 s4, v251, 4
	v_readlane_b32 s5, v251, 5
	s_add_u32 s76, s4, 0x10000
	v_lshlrev_b32_e32 v6, 6, v0
	s_movk_i32 s3, 0x3c0
	s_addc_u32 s77, s5, 0
	v_bfe_u32 v3, v0, 4, 2
	v_and_or_b32 v4, v6, s3, v4
	s_waitcnt vmcnt(6)
	s_add_u32 s78, s4, 0x20800
	v_lshlrev_b32_e32 v158, 3, v3
	v_bitop3_b32 v159, s2, v4, v5 bitop3:0xf6
	s_addc_u32 s79, s5, 0
	s_add_i32 s93, 0, 0x10000
	s_add_i32 s94, 0, 0x14000
	v_add_u32_e32 v179, 0, v2
	v_mbcnt_lo_u32_b32 v2, -1, 0
	v_cmp_eq_u32_e64 s[2:3], 0, v3
	v_lshl_or_b32 v176, s75, 5, v158
	v_mov_b64_e32 v[160:161], 0x294
	v_mov_b64_e32 v[162:163], 0x293
	v_add_u32_e32 v177, s93, v159
	v_add_u32_e32 v178, s94, v159
	v_lshlrev_b32_e32 v164, 2, v158
	v_mov_b32_e32 v180, 0x358637bd
	s_mov_b32 s95, 0xf800000
	v_mov_b32_e32 v181, 0x260
	v_mov_b32_e32 v182, 0x3e38aa3b
	v_mbcnt_hi_u32_b32 v183, -1, v2
	s_barrier
	s_branch .LBB0_145

; #define PG8_STAGE(bufoff, gbase, voff) do { _Pragma("unroll") for (int _i = 0; _i < 2; ++_i) \
;         __builtin_amdgcn_global_load_lds((const unsigned*)((const char*)(gbase) + (voff)[_i]), (PG8_LAS unsigned*)(lds + (bufoff) + ldsw + _i * 8192), 16, 0, 0); } while (0)
; #define PG8_WAIT_V(n) asm volatile("s_waitcnt vmcnt(" #n ")" ::: "memory")
; #define PG8_BAR __builtin_amdgcn_s_barrier()
; template <class Epi, class Sched, bool ALIGN_EPI = false, bool SP2 = false>
; __device__ __forceinline__ void gemm_phase(PG8_LAS unsigned char* lds, const Gemm g, const Sched& S, const Epi& E) {
;     ...
;         PG8_STAGE(PG8_SB(0, 0), cB, voffB); PG8_STAGE(PG8_SB(0, 1), cB + hstep, voffB); PG8_STAGE(PG8_SA(0, 0), cA, voffA); PG8_STAGE(PG8_SA(0, 1), cA + hstep, voffA);
;         if (wr == 1) PG8_BAR;
;         PG8_WAIT_V(2); PG8_BAR;
;         PG8_STAGE(PG8_SB(1, 0), cB + kstep, voffB); PG8_STAGE(PG8_SA(1, 0), cA + kstep, voffA); PG8_STAGE(PG8_SB(1, 1), cB + hstep + kstep, voffB);
;         PG8_WAIT_V(6); PG8_BAR;
.LBB0_871:
	s_mov_b64 s[28:29], 0x4000
	s_add_i32 m0, s1, 0x18000
	v_lshl_add_u64 v[6:7], v[2:3], 0, s[28:29]
	s_mov_b64 s[30:31], 0x6000
	global_load_lds_dwordx4 v[6:7], off
	v_lshl_add_u64 v[6:7], v[2:3], 0, s[30:31]
	s_add_i32 m0, s1, 0x1a000
	s_add_i32 s69, s1, 0x8000
	global_load_lds_dwordx4 v[6:7], off
	v_lshl_add_u64 v[6:7], v[4:5], 0, s[28:29]
	s_mov_b32 m0, s69
	s_add_i32 s70, s1, 0xa000
	global_load_lds_dwordx4 v[6:7], off
	v_lshl_add_u64 v[4:5], v[4:5], 0, s[30:31]
	s_mov_b32 m0, s70
	s_mov_b64 s[34:35], 0x44000
	global_load_lds_dwordx4 v[4:5], off
	s_add_i32 m0, s1, 0x1c000
	v_lshl_add_u64 v[4:5], v[2:3], 0, s[34:35]
	s_mov_b64 s[36:37], 0x46000
	global_load_lds_dwordx4 v[4:5], off
	v_lshl_add_u64 v[2:3], v[2:3], 0, s[36:37]
	s_add_i32 m0, s1, 0x1e000
	s_lshl_b32 s4, s4, 5
	global_load_lds_dwordx4 v[2:3], off
	s_waitcnt vmcnt(8)
	s_barrier
	v_and_b32_e32 v1, 15, v0
	v_and_b32_e32 v3, 48, v0
	v_lshlrev_b32_e32 v5, 2, v0
	s_and_b32 s72, s4, 0x60
	v_lshlrev_b32_e32 v6, 6, v0
	s_movk_i32 s73, 0x3c0
	s_lshl_b32 s71, s7, 6
	s_lshl_b32 s5, s7, 13
	v_lshl_or_b32 v4, v1, 6, v3
	v_and_b32_e32 v5, 32, v5
	v_and_or_b32 v3, v6, s73, v3
	s_lshl_b32 s4, s72, 7
	v_bitop3_b32 v4, v4, s5, v5 bitop3:0xde
	v_bitop3_b32 v160, s4, v3, v5 bitop3:0xf6
	s_cmpk_lt_u32 s6, 0x100
	v_readlane_b32 s4, v251, 4
	s_cselect_b64 s[38:39], -1, 0
	v_readlane_b32 s5, v251, 5
	s_add_u32 s40, s4, 0x2000000
	s_addc_u32 s41, s5, 0
	s_add_u32 s42, s4, 0xba00000
	s_addc_u32 s43, s5, 0
	s_add_u32 s44, s4, 0x41800
	s_addc_u32 s45, s5, 0
	s_add_u32 s46, s4, 0x31000
	v_bfe_u32 v2, v0, 4, 2
	s_waitcnt vmcnt(6)
	s_addc_u32 s47, s5, 0
	s_lshl_b32 s6, s7, 3
	v_lshlrev_b32_e32 v157, 3, v2
	v_cmp_eq_u32_e64 s[4:5], 0, v2
	s_and_b32 s74, s6, 8
	v_readlane_b32 s6, v251, 3
	s_add_i32 s77, 0, 0x10000
	s_add_i32 s78, 0, 0x14000
	v_mbcnt_lo_u32_b32 v2, -1, 0
	s_ashr_i32 s75, s6, 31
	s_ashr_i32 s76, s96, 31
	v_mov_b64_e32 v[140:141], 0x100
	v_mov_b64_e32 v[142:143], 0xff
	v_add_u32_e32 v161, s77, v160
	v_add_u32_e32 v162, s78, v160
	v_add_u32_e32 v163, 0, v4
	v_mbcnt_hi_u32_b32 v164, -1, v2
	s_barrier
	s_branch .LBB0_874

; #define PG8_STAGE(bufoff, gbase, voff) do { _Pragma("unroll") for (int _i = 0; _i < 2; ++_i) \
;         __builtin_amdgcn_global_load_lds((const unsigned*)((const char*)(gbase) + (voff)[_i]), (PG8_LAS unsigned*)(lds + (bufoff) + ldsw + _i * 8192), 16, 0, 0); } while (0)
; #define PG8_WAIT_V(n) asm volatile("s_waitcnt vmcnt(" #n ")" ::: "memory")
; #define PG8_BAR __builtin_amdgcn_s_barrier()
; template <class Epi, class Sched, bool ALIGN_EPI = false, bool SP2 = false>
; __device__ __forceinline__ void gemm_phase(PG8_LAS unsigned char* lds, const Gemm g, const Sched& S, const Epi& E) {
;     ...
;         PG8_STAGE(PG8_SB(0, 0), cB, voffB); PG8_STAGE(PG8_SB(0, 1), cB + hstep, voffB); PG8_STAGE(PG8_SA(0, 0), cA, voffA); PG8_STAGE(PG8_SA(0, 1), cA + hstep, voffA);
;         if (wr == 1) PG8_BAR;
;         PG8_WAIT_V(2); PG8_BAR;
;         PG8_STAGE(PG8_SB(1, 0), cB + kstep, voffB); PG8_STAGE(PG8_SA(1, 0), cA + kstep, voffA); PG8_STAGE(PG8_SB(1, 1), cB + hstep + kstep, voffB);
;         PG8_WAIT_V(6); PG8_BAR;
.LBB0_971:
	s_mov_b64 s[18:19], 0x4000
	s_add_i32 m0, s47, 0x18000
	v_lshl_add_u64 v[6:7], v[2:3], 0, s[18:19]
	s_mov_b64 s[20:21], 0x6000
	global_load_lds_dwordx4 v[6:7], off
	v_lshl_add_u64 v[6:7], v[2:3], 0, s[20:21]
	s_add_i32 m0, s47, 0x1a000
	s_add_i32 s56, s47, 0x8000
	global_load_lds_dwordx4 v[6:7], off
	v_lshl_add_u64 v[6:7], v[4:5], 0, s[18:19]
	s_mov_b32 m0, s56
	s_add_i32 s57, s47, 0xa000
	global_load_lds_dwordx4 v[6:7], off
	v_lshl_add_u64 v[4:5], v[4:5], 0, s[20:21]
	s_mov_b32 m0, s57
	s_mov_b64 s[22:23], 0x44000
	global_load_lds_dwordx4 v[4:5], off
	s_add_i32 m0, s47, 0x1c000
	v_lshl_add_u64 v[4:5], v[2:3], 0, s[22:23]
	s_mov_b64 s[24:25], 0x46000
	global_load_lds_dwordx4 v[4:5], off
	v_lshl_add_u64 v[2:3], v[2:3], 0, s[24:25]
	s_add_i32 m0, s47, 0x1e000
	s_sext_i32_i16 s5, s2
	global_load_lds_dwordx4 v[2:3], off
	s_waitcnt vmcnt(8)
	s_barrier
	s_and_b32 s2, s28, 3
	v_and_b32_e32 v1, 15, v0
	v_and_b32_e32 v142, 48, v0
	s_lshl_b32 s58, s3, 6
	s_lshl_b32 s28, s3, 13
	v_lshlrev_b32_e32 v3, 2, v0
	s_lshl_b32 s59, s2, 5
	s_lshl_b32 s2, s2, 12
	v_lshl_or_b32 v2, v1, 6, v142
	v_and_b32_e32 v3, 32, v3
	s_cmpk_lt_u32 s36, 0x100
	v_readlane_b32 s34, v251, 4
	v_bitop3_b32 v2, v2, s28, v3 bitop3:0xde
	s_cselect_b64 s[28:29], -1, 0
	v_readlane_b32 s35, v251, 5
	s_add_u32 s30, s34, 0x31000
	v_lshlrev_b32_e32 v4, 6, v0
	s_movk_i32 s60, 0x3c0
	s_addc_u32 s31, s35, 0
	v_and_or_b32 v4, v4, s60, v142
	s_add_u32 s34, s34, 0xdc00000
	v_bitop3_b32 v143, s2, v4, v3 bitop3:0xf6
	s_addc_u32 s35, s35, 0
	s_lshl_b32 s2, s3, 3
	s_bfe_u32 s61, s36, 0x10006
	s_and_b32 s2, s2, 8
	s_waitcnt vmcnt(6)
	s_or_b32 s2, s2, s61
	s_lshl_b32 s62, s2, 10
	v_readlane_b32 s2, v251, 3
	s_add_i32 s64, 0, 0x10000
	s_add_i32 s65, 0, 0x14000
	s_ashr_i32 s63, s2, 31
	v_mov_b64_e32 v[134:135], 0x5ac
	v_mov_b64_e32 v[136:137], 0x5ab
	v_add_u32_e32 v144, s64, v143
	v_add_u32_e32 v145, s65, v143
	v_add_u32_e32 v146, 0, v2
	v_mov_b32_e32 v147, 0x358637bd
	s_mov_b32 s66, 0xf800000
	v_mov_b32_e32 v148, 0x260
	s_barrier
	s_branch .LBB0_974

; #define PG8_STAGE(bufoff, gbase, voff) do { _Pragma("unroll") for (int _i = 0; _i < 2; ++_i) \
;         __builtin_amdgcn_global_load_lds((const unsigned*)((const char*)(gbase) + (voff)[_i]), (PG8_LAS unsigned*)(lds + (bufoff) + ldsw + _i * 8192), 16, 0, 0); } while (0)
; #define PG8_WAIT_V(n) asm volatile("s_waitcnt vmcnt(" #n ")" ::: "memory")
; #define PG8_BAR __builtin_amdgcn_s_barrier()
; template <class Epi, class Sched, bool ALIGN_EPI = false, bool SP2 = false>
; __device__ __forceinline__ void gemm_phase(PG8_LAS unsigned char* lds, const Gemm g, const Sched& S, const Epi& E) {
;     ...
;         PG8_STAGE(PG8_SB(0, 0), cB, voffB); PG8_STAGE(PG8_SB(0, 1), cB + hstep, voffB); PG8_STAGE(PG8_SA(0, 0), cA, voffA); PG8_STAGE(PG8_SA(0, 1), cA + hstep, voffA);
;         if (wr == 1) PG8_BAR;
;         PG8_WAIT_V(2); PG8_BAR;
;         PG8_STAGE(PG8_SB(1, 0), cB + kstep, voffB); PG8_STAGE(PG8_SA(1, 0), cA + kstep, voffA); PG8_STAGE(PG8_SB(1, 1), cB + hstep + kstep, voffB);
;         PG8_WAIT_V(6); PG8_BAR;
.LBB0_1410:
	s_lshl_b32 s3, s3, 5
	s_mov_b64 s[20:21], 0x4000
	s_and_b32 s45, s3, 0x60
	s_add_i32 m0, s39, 0x18000
	v_lshl_add_u64 v[4:5], v[2:3], 0, s[20:21]
	s_lshl_b32 s44, s0, 6
	s_lshl_b32 s28, s0, 13
	s_lshl_b32 s3, s45, 7
	global_load_lds_dwordx4 v[4:5], off
	s_add_i32 m0, s39, 0x1a000
	s_mov_b64 s[22:23], 0x6000
	s_add_u32 s24, s12, 0x4000
	v_lshl_add_u64 v[4:5], v[2:3], 0, s[22:23]
	s_addc_u32 s25, s13, 0
	s_add_i32 s46, s39, 0x8000
	global_load_lds_dwordx4 v[4:5], off
	v_lshl_add_u64 v[4:5], s[24:25], 0, v[128:129]
	s_mov_b32 m0, s46
	s_add_i32 s47, s39, 0xa000
	global_load_lds_dwordx4 v[4:5], off
	v_lshl_add_u64 v[4:5], s[24:25], 0, v[130:131]
	s_mov_b32 m0, s47
	s_mov_b64 s[24:25], 0xb4000
	global_load_lds_dwordx4 v[4:5], off
	s_add_i32 m0, s39, 0x1c000
	v_lshl_add_u64 v[4:5], v[2:3], 0, s[24:25]
	s_mov_b64 s[26:27], 0xb6000
	global_load_lds_dwordx4 v[4:5], off
	v_lshl_add_u64 v[2:3], v[2:3], 0, s[26:27]
	s_add_i32 m0, s39, 0x1e000
	v_lshrrev_b32_e32 v1, 1, v0
	global_load_lds_dwordx4 v[2:3], off
	s_waitcnt vmcnt(8)
	s_barrier
	v_and_b32_e32 v141, 24, v1
	v_and_b32_e32 v140, 15, v0
	v_lshlrev_b32_e32 v1, 1, v141
	v_lshlrev_b32_e32 v3, 2, v0
	v_lshlrev_b32_e32 v0, 6, v0
	s_movk_i32 s48, 0x3c0
	v_and_b32_e32 v3, 32, v3
	v_and_or_b32 v0, v0, s48, v1
	v_lshl_or_b32 v2, v140, 6, v1
	v_bitop3_b32 v142, s3, v0, v3 bitop3:0xf6
	s_cmpk_lt_u32 s2, 0x100
	v_readlane_b32 s2, v251, 4
	v_bitop3_b32 v2, v2, s28, v3 bitop3:0xde
	s_cselect_b64 s[28:29], -1, 0
	v_readlane_b32 s3, v251, 5
	s_add_u32 s30, s2, 0xba00000
	s_waitcnt vmcnt(6)
	s_addc_u32 s31, s3, 0
	s_lshl_b32 s0, s0, 3
	s_and_b32 s49, s0, 8
	v_readlane_b32 s0, v251, 3
	s_add_i32 s51, 0, 0x10000
	s_add_i32 s52, 0, 0x14000
	s_sext_i32_i8 s56, s1
	s_ashr_i32 s50, s0, 31
	v_mov_b64_e32 v[132:133], 0x100
	v_mov_b64_e32 v[134:135], 0xff
	v_add_u32_e32 v143, s51, v142
	v_add_u32_e32 v144, s52, v142
	v_add_u32_e32 v145, 0, v2
	s_barrier
	s_branch .LBB0_1413
